# P4: co-resident workgroups take conv items and attention in opposite order (HW_ID workgroup-slot bit), so HBM-bound conv of one overlaps MFMA-bound attention of the other
# baseline (speedup 1.0000x reference)
; template <class BG>
; DI void xcd_barrier_bg(const XcdBarrier b, char* smem, BG bg) {
;   asm volatile("s_waitcnt vmcnt(0)" ::: "memory");
;   __syncthreads();
;   volatile unsigned* sst = (volatile unsigned*)(smem + 12);
;   unsigned mygen = 0u;
;   if (threadIdx.x == 0) {
;     unsigned* bar = b.bar;
;     __builtin_amdgcn_s_waitcnt(0);
;     unsigned nloc = b.st[0], nx = b.st[1];
;     if (nloc == 0u) { xcd_barrier_complete(bar, b.x, nloc, nx); b.st[0] = nloc; b.st[1] = nx; }
.LBB0_535:
	s_mov_b32 s97, 0
	s_cmp_lt_i32 s38, 5
	s_cselect_b64 s[42:43], -1, 0
	s_cmp_gt_i32 s38, 4
	s_cselect_b64 s[2:3], -1, 0
	s_cmp_lt_i32 s39, 5
	s_cselect_b64 s[4:5], -1, 0
	s_or_b64 s[2:3], s[2:3], s[4:5]
	s_and_b64 vcc, exec, s[2:3]
	s_cbranch_vccnz .LBB0_650
	s_andn2_b64 vcc, exec, s[40:41]
	s_cbranch_vccnz .LBB0_628
	s_waitcnt vmcnt(0)
	v_mov_b32_e32 v1, 0
	v_cmp_eq_u32_e64 s[2:3], 0, v0
	s_waitcnt lgkmcnt(0)
	s_barrier
	s_and_saveexec_b64 s[40:41], s[2:3]
	s_cbranch_execz .LBB0_577
	v_mov_b32_e32 v1, 0
	s_waitcnt vmcnt(0) expcnt(0) lgkmcnt(0)
	ds_read_b32 v4, v1
	ds_read_b32 v2, v1 offset:4
	s_waitcnt lgkmcnt(1)
	v_cmp_ne_u32_e32 vcc, 0, v4
	s_cbranch_vccnz .LBB0_554
	s_load_dwordx2 s[4:5], s[0:1], 0xc0
	s_load_dword s8, s[0:1], 0xc8
	s_mov_b64 s[6:7], 0x1000
	s_waitcnt lgkmcnt(0)
	v_lshl_add_u64 v[2:3], v[188:189], 0, s[6:7]
	s_mov_b32 s24, 1
	s_mul_i32 s13, s5, s4
	s_mov_b64 s[4:5], 0x1100
	v_lshl_add_u64 v[4:5], v[188:189], 0, s[4:5]
	s_mov_b64 s[4:5], 0x1200
	v_lshl_add_u64 v[6:7], v[188:189], 0, s[4:5]
	s_mov_b64 s[4:5], 0x1300
	s_mul_i32 s13, s13, s8
	v_lshl_add_u64 v[8:9], v[188:189], 0, s[4:5]
	s_mov_b64 s[4:5], 0
	s_branch .LBB0_542

; DI void conv_items(const Params& p) {
;   const u16* P = (const u16*)(p.ws + WS_P); u16* MG = (u16*)(p.ws + WS_MG);
;   const float* cw = p.in[6];
;   const int lane = threadIdx.x & 63;
;   for (int j2 = blockIdx.x; j2 < 512; j2 += gridDim.x) {
;     const int wv = j2 * 4 + (threadIdx.x >> 6);
;     const int quad = wv & 1, run = wv >> 1;
;     const int row0 = run * 8, t0 = row0 & (S_ - 1);
;     const int ch = (quad * 4 + (lane >> 4)) * 128 + (lane & 15) * 8;
;     float w0[8], w1[8], w2[8];
; #pragma unroll
;     for (int q = 0; q < 2; ++q) {
;       const float4 a = *(const float4*)(cw + ch + q * 4), b2 = *(const float4*)(cw + 1024 + ch + q * 4), c2 = *(const float4*)(cw + 2048 + ch + q * 4);
;       w0[q * 4] = a.x; w0[q * 4 + 1] = a.y; w0[q * 4 + 2] = a.z; w0[q * 4 + 3] = a.w;
;       w1[q * 4] = b2.x; w1[q * 4 + 1] = b2.y; w1[q * 4 + 2] = b2.z; w1[q * 4 + 3] = b2.w;
;       w2[q * 4] = c2.x; w2[q * 4 + 1] = c2.y; w2[q * 4 + 2] = c2.z; w2[q * 4 + 3] = c2.w;
;     }
.LBB0_628:
	s_cmpk_gt_i32 s12, 0x1ff
	s_cbranch_scc1 .LBB0_650
	s_cmp_lg_u32 s97, 0
	s_cbranch_scc1 .Lp4_decided
	s_getreg_b32 s96, hwreg(HW_REG_HW_ID, 16, 4)
	s_bitcmp1_b32 s96, 0
	s_cselect_b32 s97, 1, 3
.Lp4_decided:
	v_mbcnt_lo_u32_b32 v3, -1, 0
	v_mbcnt_hi_u32_b32 v76, -1, v3
	v_and_b32_e32 v4, 64, v76
	v_xor_b32_e32 v3, 8, v76
	v_add_u32_e32 v77, 64, v4
	v_cmp_lt_i32_e32 vcc, v3, v77
	v_lshlrev_b32_e32 v78, 3, v0
	s_load_dword s13, s[0:1], 0xc0
	v_cndmask_b32_e32 v3, v76, v3, vcc
	v_lshlrev_b32_e32 v79, 2, v3
	v_xor_b32_e32 v3, 4, v76
	v_cmp_lt_i32_e32 vcc, v3, v77
	s_waitcnt lgkmcnt(0)
	v_and_b32_e32 v2, 0x3f8, v78
	s_add_u32 s2, s82, 0x8538000
	v_cndmask_b32_e32 v3, v76, v3, vcc
	v_lshlrev_b32_e32 v80, 2, v3
	v_xor_b32_e32 v3, 2, v76
	v_cmp_lt_i32_e32 vcc, v3, v77
	v_mov_b32_e32 v27, 0
	v_lshlrev_b32_e32 v26, 2, v2
	v_cndmask_b32_e32 v3, v76, v3, vcc
	v_lshlrev_b32_e32 v81, 2, v3
	v_xor_b32_e32 v3, 1, v76
	s_addc_u32 s3, s83, 0
	v_lshrrev_b32_e32 v1, 4, v0
	v_lshl_add_u64 v[28:29], s[68:69], 0, v[26:27]
	s_mov_b64 s[4:5], 0x1000
	v_cmp_lt_i32_e32 vcc, v3, v77
	v_and_b32_e32 v1, 12, v1
	v_lshl_add_u64 v[30:31], v[28:29], 0, s[4:5]
	s_mov_b64 s[4:5], 0x2000
	v_cndmask_b32_e32 v3, v76, v3, vcc
	s_add_u32 s6, s0, 0xc0
	v_lshl_add_u64 v[32:33], v[28:29], 0, s[4:5]
	s_waitcnt vmcnt(6)
	v_lshlrev_b32_e32 v82, 2, v3
	s_addc_u32 s7, s1, 0
	v_lshlrev_b32_e32 v34, 1, v2
	v_mov_b32_e32 v35, v27
	v_lshl_or_b32 v83, s12, 4, v1
	s_lshl_b32 s14, s13, 4
	v_mov_b32_e32 v84, 0x7f8
	s_movk_i32 s15, 0x2080
	v_lshlrev_b32_e32 v26, 1, v2
	s_movk_i32 s16, 0x1000
	s_mov_b32 s17, 0x8538000
	s_mov_b32 s18, 0x8539000
	v_mov_b32_e32 v85, 0x358637bd
	s_mov_b32 s19, 0x800000
	s_mov_b32 s20, 0x853a000
	s_mov_b32 s21, 0x853b000
	s_mov_b32 s22, 0x10639000
	s_mov_b32 s23, 0x853c000
	s_mov_b32 s24, 0x853d000
	s_mov_b32 s25, 0x853e000
	s_mov_b32 s26, 0x853f000
	s_mov_b32 s27, 0x1063b000
	s_mov_b64 s[4:5], 0x4000
	s_mov_b64 s[8:9], 0x8200
	s_mov_b32 s28, s12
	s_cmp_eq_u32 s97, 1
	s_cbranch_scc1 .Lp4_attn

; DI unsigned pk2(float a, float b) { f2_t v = {a, b}; bf2_t r = __builtin_convertvector(v, bf2_t); return __builtin_bit_cast(unsigned, r); }
; DI float bflo(unsigned u) { return __uint_as_float(u << 16); }
; DI float bfhi(unsigned u) { return __uint_as_float(u & 0xffff0000u); }
; DI void conv_items(const Params& p) {
;     ...
;     for (int tt = 0; tt < 8; ++tt) {
;       const size_t ro = (size_t)(row0 + tt) * INC;
;       const u32x4 bb = *(const u32x4*)(P + ro + ch), cc = *(const u32x4*)(P + ro + 1024 + ch), hh = *(const u32x4*)(P + ro + 2048 + ch);
;       float y[8];
;       float ss = 0.f;
; #pragma unroll
;       for (int d = 0; d < 4; ++d) {
;         const float za = bflo(cc[d]) * bflo(hh[d]), zb = bfhi(cc[d]) * bfhi(hh[d]);
;         y[2 * d] = bflo(bb[d]) * (w0[2 * d] * zm2[2 * d] + w1[2 * d] * zm1[2 * d] + w2[2 * d] * za);
;         y[2 * d + 1] = bfhi(bb[d]) * (w0[2 * d + 1] * zm2[2 * d + 1] + w1[2 * d + 1] * zm1[2 * d + 1] + w2[2 * d + 1] * zb);
;         zm2[2 * d] = zm1[2 * d]; zm2[2 * d + 1] = zm1[2 * d + 1]; zm1[2 * d] = za; zm1[2 * d + 1] = zb;
;         ss += y[2 * d] * y[2 * d] + y[2 * d + 1] * y[2 * d + 1];
;       }
;       ss += __shfl_xor(ss, 8); ss += __shfl_xor(ss, 4); ss += __shfl_xor(ss, 2); ss += __shfl_xor(ss, 1);
;       const float rstd = rsqrtf(ss * (1.f / 128.f) + EPS);
;       const u32x4 o = {pk2(y[0] * rstd, y[1] * rstd), pk2(y[2] * rstd, y[3] * rstd), pk2(y[4] * rstd, y[5] * rstd), pk2(y[6] * rstd, y[7] * rstd)};
;       *(u32x4*)(MG + (size_t)(row0 + tt) * D_ + ch) = o;
.LBB0_633:
	s_nop 0
	v_lshl_add_u64 v[58:59], v[38:39], 0, v[34:35]
	v_add_co_u32_e32 v70, vcc, s17, v58
	s_waitcnt vmcnt(3)
	v_pk_mul_f32 v[60:61], v[12:13], v[46:47]
	v_addc_co_u32_e32 v71, vcc, 0, v59, vcc
	v_add_co_u32_e32 v72, vcc, s18, v58
	v_pk_mul_f32 v[64:65], v[10:11], v[44:45]
	s_nop 0
	v_addc_co_u32_e32 v73, vcc, 0, v59, vcc
	global_load_dwordx4 v[86:89], v[70:71], off offset:2048
	global_load_dwordx4 v[90:93], v[72:73], off
	global_load_dwordx4 v[94:97], v[72:73], off offset:-4096
	s_waitcnt vmcnt(5)
	v_pk_mul_f32 v[66:67], v[16:17], v[42:43]
	v_pk_mul_f32 v[68:69], v[14:15], v[40:41]
	v_pk_fma_f32 v[62:63], v[4:5], v[50:51], v[60:61]
	v_pk_fma_f32 v[64:65], v[2:3], v[54:55], v[64:65]
	v_pk_fma_f32 v[66:67], v[8:9], v[48:49], v[66:67]
	v_pk_fma_f32 v[68:69], v[6:7], v[52:53], v[68:69]
	v_lshl_add_u64 v[56:57], v[36:37], 0, v[34:35]
	v_add_co_u32_e32 v48, vcc, s22, v56
	s_add_i32 s10, s10, -4
	s_nop 0
	v_addc_co_u32_e32 v49, vcc, 0, v57, vcc
	v_add_co_u32_e32 v50, vcc, s20, v58
	v_lshl_add_u64 v[36:37], v[36:37], 0, s[4:5]
	s_nop 0
	v_addc_co_u32_e32 v51, vcc, 0, v59, vcc
	v_add_co_u32_e32 v52, vcc, s21, v58
	v_lshl_add_u64 v[38:39], v[38:39], 0, s[8:9]
	s_nop 0
	v_addc_co_u32_e32 v53, vcc, 0, v59, vcc
	v_add_co_u32_e32 v54, vcc, s23, v58
	s_cmp_eq_u32 s10, 0
	s_nop 0
	v_addc_co_u32_e32 v55, vcc, 0, v59, vcc
	v_add_co_u32_e32 v60, vcc, s24, v58
	s_waitcnt vmcnt(2)
	v_lshlrev_b32_e32 v70, 16, v89
	s_waitcnt vmcnt(1)
	v_lshlrev_b32_e32 v72, 16, v93
	v_and_b32_e32 v73, 0xffff0000, v93
	v_and_b32_e32 v71, 0xffff0000, v89
	s_waitcnt vmcnt(0)
	v_lshlrev_b32_e32 v98, 16, v97
	v_and_b32_e32 v99, 0xffff0000, v97
	v_lshlrev_b32_e32 v100, 16, v88
	v_and_b32_e32 v101, 0xffff0000, v88
	v_lshlrev_b32_e32 v88, 16, v92
	v_and_b32_e32 v89, 0xffff0000, v92
	v_lshlrev_b32_e32 v92, 16, v96
	v_and_b32_e32 v93, 0xffff0000, v96
	v_lshlrev_b32_e32 v96, 16, v87
	v_and_b32_e32 v97, 0xffff0000, v87
	v_lshlrev_b32_e32 v102, 16, v91
	v_and_b32_e32 v103, 0xffff0000, v91
	v_lshlrev_b32_e32 v106, 16, v86
	v_and_b32_e32 v107, 0xffff0000, v86
	v_lshlrev_b32_e32 v86, 16, v90
	v_and_b32_e32 v87, 0xffff0000, v90
	v_pk_mul_f32 v[70:71], v[70:71], v[72:73]
	v_pk_mul_f32 v[72:73], v[100:101], v[88:89]
	v_pk_mul_f32 v[88:89], v[96:97], v[102:103]
	v_pk_mul_f32 v[86:87], v[106:107], v[86:87]
	v_lshlrev_b32_e32 v104, 16, v95
	v_and_b32_e32 v105, 0xffff0000, v95
	v_lshlrev_b32_e32 v90, 16, v94
	v_and_b32_e32 v91, 0xffff0000, v94
	v_pk_fma_f32 v[62:63], v[20:21], v[70:71], v[62:63]
	v_pk_fma_f32 v[64:65], v[18:19], v[72:73], v[64:65]
	v_pk_fma_f32 v[66:67], v[24:25], v[88:89], v[66:67]
	v_pk_fma_f32 v[68:69], v[22:23], v[86:87], v[68:69]
	v_pk_mul_f32 v[96:97], v[10:11], v[72:73]
	v_pk_mul_f32 v[102:103], v[14:15], v[86:87]
	v_pk_mul_f32 v[62:63], v[62:63], v[98:99]
	v_pk_mul_f32 v[64:65], v[64:65], v[92:93]
	v_pk_mul_f32 v[66:67], v[66:67], v[104:105]
	v_pk_mul_f32 v[68:69], v[68:69], v[90:91]
	v_pk_mul_f32 v[94:95], v[12:13], v[70:71]
	v_pk_mul_f32 v[100:101], v[16:17], v[88:89]
	v_pk_fma_f32 v[92:93], v[2:3], v[44:45], v[96:97]
	v_pk_fma_f32 v[96:97], v[6:7], v[40:41], v[102:103]
	v_mov_b32_e32 v40, v62
	v_mov_b32_e32 v41, v64
	v_mov_b32_e32 v44, v68
	v_mov_b32_e32 v45, v66
	v_pk_fma_f32 v[90:91], v[4:5], v[46:47], v[94:95]
	v_pk_fma_f32 v[94:95], v[8:9], v[42:43], v[100:101]
	v_mov_b32_e32 v42, v63
	v_mov_b32_e32 v43, v65
	v_mov_b32_e32 v46, v69
	v_mov_b32_e32 v47, v67
	v_pk_mul_f32 v[40:41], v[40:41], v[40:41]
	v_pk_mul_f32 v[44:45], v[44:45], v[44:45]
	v_pk_fma_f32 v[40:41], v[42:43], v[42:43], v[40:41]
	v_pk_fma_f32 v[42:43], v[46:47], v[46:47], v[44:45]
	v_addc_co_u32_e32 v61, vcc, 0, v59, vcc
	v_add_f32_e32 v42, v42, v43
	v_add_f32_e32 v41, v41, v42
	v_add_f32_e32 v40, v40, v41
	ds_bpermute_b32 v41, v79, v40
	v_add_co_u32_e32 v56, vcc, s27, v56
	s_waitcnt lgkmcnt(0)
	v_add_f32_e32 v40, v40, v41
	ds_bpermute_b32 v41, v80, v40
	v_addc_co_u32_e32 v57, vcc, 0, v57, vcc
	v_add_co_u32_e32 v74, vcc, s25, v58
	s_waitcnt lgkmcnt(0)
	v_add_f32_e32 v40, v40, v41
	ds_bpermute_b32 v41, v81, v40
	v_addc_co_u32_e32 v75, vcc, 0, v59, vcc
	v_add_co_u32_e32 v58, vcc, s26, v58
	s_waitcnt lgkmcnt(0)
	v_add_f32_e32 v40, v40, v41
	ds_bpermute_b32 v41, v82, v40
	v_addc_co_u32_e32 v59, vcc, 0, v59, vcc
	s_waitcnt lgkmcnt(0)
	v_add_f32_e32 v40, v40, v41
	v_fmamk_f32 v40, v40, 0x3c000000, v85
	v_mul_f32_e32 v41, 0x4b800000, v40
	v_cmp_gt_f32_e32 vcc, s19, v40
	s_nop 1
	v_cndmask_b32_e32 v40, v40, v41, vcc
	v_rsq_f32_e32 v40, v40
	s_nop 0
	v_mul_f32_e32 v41, 0x45800000, v40
	v_cndmask_b32_e32 v40, v40, v41, vcc
	v_pk_mul_f32 v[42:43], v[68:69], v[40:41] op_sel_hi:[1,0]
	v_pk_mul_f32 v[44:45], v[66:67], v[40:41] op_sel_hi:[1,0]
	v_pk_mul_f32 v[46:47], v[64:65], v[40:41] op_sel_hi:[1,0]
	v_pk_mul_f32 v[62:63], v[62:63], v[40:41] op_sel_hi:[1,0]
	v_cvt_pk_bf16_f32 v40, v42, v43
	v_cvt_pk_bf16_f32 v41, v44, v45
	v_cvt_pk_bf16_f32 v42, v46, v47
	v_cvt_pk_bf16_f32 v43, v62, v63
	global_store_dwordx4 v[48:49], v[40:43], off offset:-4096
	global_load_dwordx4 v[40:43], v[50:51], off offset:2176
	s_nop 0
	global_load_dwordx4 v[44:47], v[52:53], off offset:128
	global_load_dwordx4 v[62:65], v[50:51], off offset:128
	s_waitcnt vmcnt(2)
	v_lshlrev_b32_e32 v50, 16, v43
	s_waitcnt vmcnt(1)
	v_lshlrev_b32_e32 v52, 16, v47
	v_and_b32_e32 v53, 0xffff0000, v47
	v_and_b32_e32 v51, 0xffff0000, v43
	s_waitcnt vmcnt(0)
; DI unsigned pk2(float a, float b) { f2_t v = {a, b}; bf2_t r = __builtin_convertvector(v, bf2_t); return __builtin_bit_cast(unsigned, r); }
; DI float bflo(unsigned u) { return __uint_as_float(u << 16); }
; DI float bfhi(unsigned u) { return __uint_as_float(u & 0xffff0000u); }
; DI void conv_items(const Params& p) {
;     ...
;     for (int tt = 0; tt < 8; ++tt) {
;       const size_t ro = (size_t)(row0 + tt) * INC;
;       const u32x4 bb = *(const u32x4*)(P + ro + ch), cc = *(const u32x4*)(P + ro + 1024 + ch), hh = *(const u32x4*)(P + ro + 2048 + ch);
;       float y[8];
;       float ss = 0.f;
; #pragma unroll
;       for (int d = 0; d < 4; ++d) {
;         const float za = bflo(cc[d]) * bflo(hh[d]), zb = bfhi(cc[d]) * bfhi(hh[d]);
;         y[2 * d] = bflo(bb[d]) * (w0[2 * d] * zm2[2 * d] + w1[2 * d] * zm1[2 * d] + w2[2 * d] * za);
;         y[2 * d + 1] = bfhi(bb[d]) * (w0[2 * d + 1] * zm2[2 * d + 1] + w1[2 * d + 1] * zm1[2 * d + 1] + w2[2 * d + 1] * zb);
;         zm2[2 * d] = zm1[2 * d]; zm2[2 * d + 1] = zm1[2 * d + 1]; zm1[2 * d] = za; zm1[2 * d + 1] = zb;
;         ss += y[2 * d] * y[2 * d] + y[2 * d + 1] * y[2 * d + 1];
;       }
;       ss += __shfl_xor(ss, 8); ss += __shfl_xor(ss, 4); ss += __shfl_xor(ss, 2); ss += __shfl_xor(ss, 1);
;       const float rstd = rsqrtf(ss * (1.f / 128.f) + EPS);
;       const u32x4 o = {pk2(y[0] * rstd, y[1] * rstd), pk2(y[2] * rstd, y[3] * rstd), pk2(y[4] * rstd, y[5] * rstd), pk2(y[6] * rstd, y[7] * rstd)};
;       *(u32x4*)(MG + (size_t)(row0 + tt) * D_ + ch) = o;
	v_lshlrev_b32_e32 v66, 16, v65
	v_and_b32_e32 v67, 0xffff0000, v65
	v_lshlrev_b32_e32 v68, 16, v42
	v_and_b32_e32 v69, 0xffff0000, v42
	v_lshlrev_b32_e32 v42, 16, v46
	v_and_b32_e32 v43, 0xffff0000, v46
	v_lshlrev_b32_e32 v98, 16, v64
	v_and_b32_e32 v99, 0xffff0000, v64
	v_lshlrev_b32_e32 v46, 16, v41
	v_and_b32_e32 v47, 0xffff0000, v41
	v_lshlrev_b32_e32 v64, 16, v45
	v_and_b32_e32 v65, 0xffff0000, v45
	v_lshlrev_b32_e32 v102, 16, v40
	v_and_b32_e32 v103, 0xffff0000, v40
	v_lshlrev_b32_e32 v104, 16, v44
	v_and_b32_e32 v105, 0xffff0000, v44
	v_pk_mul_f32 v[40:41], v[50:51], v[52:53]
	v_pk_mul_f32 v[42:43], v[68:69], v[42:43]
	v_pk_mul_f32 v[44:45], v[46:47], v[64:65]
	v_pk_mul_f32 v[46:47], v[102:103], v[104:105]
	v_lshlrev_b32_e32 v100, 16, v63
	v_and_b32_e32 v101, 0xffff0000, v63
	v_lshlrev_b32_e32 v106, 16, v62
	v_and_b32_e32 v107, 0xffff0000, v62
	v_pk_fma_f32 v[50:51], v[20:21], v[40:41], v[90:91]
	v_pk_fma_f32 v[52:53], v[18:19], v[42:43], v[92:93]
	v_pk_fma_f32 v[62:63], v[24:25], v[44:45], v[94:95]
	v_pk_fma_f32 v[64:65], v[22:23], v[46:47], v[96:97]
	v_pk_mul_f32 v[90:91], v[10:11], v[42:43]
	v_pk_mul_f32 v[50:51], v[50:51], v[66:67]
	v_pk_mul_f32 v[52:53], v[52:53], v[98:99]
	v_pk_mul_f32 v[62:63], v[62:63], v[100:101]
	v_pk_mul_f32 v[64:65], v[64:65], v[106:107]
	v_pk_mul_f32 v[68:69], v[12:13], v[40:41]
	v_pk_mul_f32 v[92:93], v[16:17], v[44:45]
	v_pk_fma_f32 v[72:73], v[2:3], v[72:73], v[90:91]
	v_mov_b32_e32 v66, v50
	v_mov_b32_e32 v67, v52
	v_mov_b32_e32 v90, v64
	v_mov_b32_e32 v91, v62
	v_pk_fma_f32 v[70:71], v[4:5], v[70:71], v[68:69]
	v_pk_fma_f32 v[88:89], v[8:9], v[88:89], v[92:93]
	v_mov_b32_e32 v68, v51
	v_mov_b32_e32 v69, v53
	v_mov_b32_e32 v92, v65
	v_mov_b32_e32 v93, v63
	v_pk_mul_f32 v[66:67], v[66:67], v[66:67]
	v_pk_mul_f32 v[90:91], v[90:91], v[90:91]
	v_pk_fma_f32 v[66:67], v[68:69], v[68:69], v[66:67]
	v_pk_fma_f32 v[68:69], v[92:93], v[92:93], v[90:91]
	v_pk_mul_f32 v[94:95], v[14:15], v[46:47]
	v_add_f32_e32 v68, v68, v69
	v_add_f32_e32 v67, v67, v68
	v_add_f32_e32 v66, v66, v67
	ds_bpermute_b32 v67, v79, v66
	v_pk_fma_f32 v[86:87], v[6:7], v[86:87], v[94:95]
	s_waitcnt lgkmcnt(0)
	v_add_f32_e32 v66, v66, v67
	ds_bpermute_b32 v67, v80, v66
	s_waitcnt lgkmcnt(0)
	v_add_f32_e32 v66, v66, v67
	ds_bpermute_b32 v67, v81, v66
	s_waitcnt lgkmcnt(0)
	v_add_f32_e32 v66, v66, v67
	ds_bpermute_b32 v67, v82, v66
	s_waitcnt lgkmcnt(0)
	v_add_f32_e32 v66, v66, v67
	v_fmamk_f32 v66, v66, 0x3c000000, v85
	v_mul_f32_e32 v67, 0x4b800000, v66
	v_cmp_gt_f32_e32 vcc, s19, v66
	s_nop 1
	v_cndmask_b32_e32 v66, v66, v67, vcc
	v_rsq_f32_e32 v66, v66
	s_nop 0
	v_mul_f32_e32 v67, 0x45800000, v66
	v_cndmask_b32_e32 v66, v66, v67, vcc
	v_pk_mul_f32 v[64:65], v[64:65], v[66:67] op_sel_hi:[1,0]
	v_pk_mul_f32 v[62:63], v[62:63], v[66:67] op_sel_hi:[1,0]
	v_pk_mul_f32 v[52:53], v[52:53], v[66:67] op_sel_hi:[1,0]
	v_pk_mul_f32 v[66:67], v[50:51], v[66:67] op_sel_hi:[1,0]
	v_cvt_pk_bf16_f32 v50, v64, v65
	v_cvt_pk_bf16_f32 v51, v62, v63
	v_cvt_pk_bf16_f32 v52, v52, v53
	v_cvt_pk_bf16_f32 v53, v66, v67
	global_store_dwordx4 v[48:49], v[50:53], off
	global_load_dwordx4 v[48:51], v[54:55], off offset:2304
	s_nop 0
	global_load_dwordx4 v[62:65], v[60:61], off offset:256
	global_load_dwordx4 v[66:69], v[54:55], off offset:256
	s_waitcnt vmcnt(2)
	v_lshlrev_b32_e32 v52, 16, v51
	s_waitcnt vmcnt(1)
	v_lshlrev_b32_e32 v54, 16, v65
	v_and_b32_e32 v55, 0xffff0000, v65
	v_and_b32_e32 v53, 0xffff0000, v51
	s_waitcnt vmcnt(0)
	v_lshlrev_b32_e32 v60, 16, v69
	v_and_b32_e32 v61, 0xffff0000, v69
	v_lshlrev_b32_e32 v90, 16, v50
	v_and_b32_e32 v91, 0xffff0000, v50
	v_lshlrev_b32_e32 v92, 16, v64
	v_and_b32_e32 v93, 0xffff0000, v64
	v_lshlrev_b32_e32 v64, 16, v68
	v_and_b32_e32 v65, 0xffff0000, v68
	v_lshlrev_b32_e32 v68, 16, v49
	v_and_b32_e32 v69, 0xffff0000, v49
	v_lshlrev_b32_e32 v94, 16, v63
	v_and_b32_e32 v95, 0xffff0000, v63
	v_lshlrev_b32_e32 v98, 16, v48
	v_and_b32_e32 v99, 0xffff0000, v48
	v_lshlrev_b32_e32 v100, 16, v62
	v_and_b32_e32 v101, 0xffff0000, v62
	v_pk_mul_f32 v[50:51], v[52:53], v[54:55]
	v_pk_mul_f32 v[54:55], v[90:91], v[92:93]
	v_pk_mul_f32 v[48:49], v[68:69], v[94:95]
	v_pk_mul_f32 v[52:53], v[98:99], v[100:101]
	v_lshlrev_b32_e32 v96, 16, v67
	v_and_b32_e32 v97, 0xffff0000, v67
	v_lshlrev_b32_e32 v62, 16, v66
	v_and_b32_e32 v63, 0xffff0000, v66
	v_pk_fma_f32 v[66:67], v[20:21], v[50:51], v[70:71]
	v_pk_fma_f32 v[68:69], v[18:19], v[54:55], v[72:73]
	v_pk_fma_f32 v[70:71], v[24:25], v[48:49], v[88:89]
	v_pk_fma_f32 v[72:73], v[22:23], v[52:53], v[86:87]
	v_pk_mul_f32 v[60:61], v[66:67], v[60:61]
	v_pk_mul_f32 v[64:65], v[68:69], v[64:65]
	v_pk_mul_f32 v[66:67], v[70:71], v[96:97]
	v_pk_mul_f32 v[62:63], v[72:73], v[62:63]
	v_mov_b32_e32 v68, v60
	v_mov_b32_e32 v69, v64
	v_mov_b32_e32 v72, v62
	v_mov_b32_e32 v73, v66
	v_mov_b32_e32 v70, v61
	v_mov_b32_e32 v71, v65
	v_mov_b32_e32 v86, v63
	v_mov_b32_e32 v87, v67
	v_pk_mul_f32 v[68:69], v[68:69], v[68:69]
	v_pk_mul_f32 v[72:73], v[72:73], v[72:73]
	v_pk_fma_f32 v[68:69], v[70:71], v[70:71], v[68:69]
	v_pk_fma_f32 v[70:71], v[86:87], v[86:87], v[72:73]
	v_pk_mul_f32 v[72:73], v[10:11], v[54:55]
	v_add_f32_e32 v70, v70, v71
	v_add_f32_e32 v69, v69, v70
	v_add_f32_e32 v68, v68, v69
	ds_bpermute_b32 v69, v79, v68
	v_pk_mul_f32 v[86:87], v[14:15], v[52:53]
	v_pk_fma_f32 v[72:73], v[2:3], v[42:43], v[72:73]
	v_pk_fma_f32 v[86:87], v[6:7], v[46:47], v[86:87]
	s_waitcnt lgkmcnt(0)
	v_add_f32_e32 v68, v68, v69
	ds_bpermute_b32 v69, v80, v68
	s_waitcnt lgkmcnt(0)
	v_add_f32_e32 v68, v68, v69
	ds_bpermute_b32 v69, v81, v68
	s_waitcnt lgkmcnt(0)
	v_add_f32_e32 v68, v68, v69
	ds_bpermute_b32 v69, v82, v68
	s_waitcnt lgkmcnt(0)
; DI void conv_items(const Params& p) {
;     ...
;     for (int tt = 0; tt < 8; ++tt) {
;       const size_t ro = (size_t)(row0 + tt) * INC;
;       const u32x4 bb = *(const u32x4*)(P + ro + ch), cc = *(const u32x4*)(P + ro + 1024 + ch), hh = *(const u32x4*)(P + ro + 2048 + ch);
;       float y[8];
;       float ss = 0.f;
; #pragma unroll
;       for (int d = 0; d < 4; ++d) {
;         const float za = bflo(cc[d]) * bflo(hh[d]), zb = bfhi(cc[d]) * bfhi(hh[d]);
;         y[2 * d] = bflo(bb[d]) * (w0[2 * d] * zm2[2 * d] + w1[2 * d] * zm1[2 * d] + w2[2 * d] * za);
;         y[2 * d + 1] = bfhi(bb[d]) * (w0[2 * d + 1] * zm2[2 * d + 1] + w1[2 * d + 1] * zm1[2 * d + 1] + w2[2 * d + 1] * zb);
;         zm2[2 * d] = zm1[2 * d]; zm2[2 * d + 1] = zm1[2 * d + 1]; zm1[2 * d] = za; zm1[2 * d + 1] = zb;
;         ss += y[2 * d] * y[2 * d] + y[2 * d + 1] * y[2 * d + 1];
;       }
;       ss += __shfl_xor(ss, 8); ss += __shfl_xor(ss, 4); ss += __shfl_xor(ss, 2); ss += __shfl_xor(ss, 1);
;       const float rstd = rsqrtf(ss * (1.f / 128.f) + EPS);
;       const u32x4 o = {pk2(y[0] * rstd, y[1] * rstd), pk2(y[2] * rstd, y[3] * rstd), pk2(y[4] * rstd, y[5] * rstd), pk2(y[6] * rstd, y[7] * rstd)};
;       *(u32x4*)(MG + (size_t)(row0 + tt) * D_ + ch) = o;
; DI void phase4(const Params& p, char* smem) {
;     ...
;   const int tid = threadIdx.x, lane = tid & 63, w = tid >> 6, qh = w & 1, kh = w >> 1, r = lane & 31, hi = lane >> 5;
;   for (int it = blockIdx.x; it < 512; it += gridDim.x) {
;     const int xq = it & 7, jq = it >> 3, bh = xq + 8 * (jq >> 4);
;     const int pi = jq & 15, h = bh & 7, b = bh >> 3;
;     for (int sub = 0; sub < 2; ++sub) {
;       const int c = sub ? (31 - pi) : pi;
;       const size_t qrow = (size_t)b * S_ + c * 64 + qh * 32 + r;
;       bf16x8 qf[12];
; #pragma unroll
;       for (int ks = 0; ks < 12; ++ks) qf[ks] = *(const bf16x8*)(Q + qrow * 1536 + h * 192 + ks * 16 + hi * 8);
;       f32x16 O[4];
; #pragma unroll
;       for (int dt = 0; dt < 4; ++dt)
; #pragma unroll
;         for (int i = 0; i < 16; ++i) O[dt][i] = 0.f;
;       float m = -1e30f, l = 0.f;
;       u32x4 kr[6]; u32x4 vr[4];
;       const u16* kg = Kb + ((size_t)b * S_ + (tid >> 2)) * 1536 + h * 192 + (tid & 3) * 8;
;       const u16* vg = VT + ((size_t)((b * 8 + h) * 128 + (tid >> 1))) * S_ + (tid & 1) * 8;
;       u16* ksw = Ks + (tid >> 2) * 200 + (tid & 3) * 8;
	v_add_f32_e32 v68, v68, v69
	v_fmamk_f32 v68, v68, 0x3c000000, v85
	v_mul_f32_e32 v69, 0x4b800000, v68
	v_cmp_gt_f32_e32 vcc, s19, v68
	s_nop 1
	v_cndmask_b32_e32 v68, v68, v69, vcc
	v_rsq_f32_e32 v68, v68
	s_nop 0
	v_mul_f32_e32 v69, 0x45800000, v68
	v_cndmask_b32_e32 v68, v68, v69, vcc
	v_pk_mul_f32 v[62:63], v[62:63], v[68:69] op_sel_hi:[1,0]
	v_pk_mul_f32 v[66:67], v[66:67], v[68:69] op_sel_hi:[1,0]
	v_pk_mul_f32 v[64:65], v[64:65], v[68:69] op_sel_hi:[1,0]
	v_pk_mul_f32 v[68:69], v[60:61], v[68:69] op_sel_hi:[1,0]
	v_cvt_pk_bf16_f32 v60, v62, v63
	v_cvt_pk_bf16_f32 v61, v66, v67
	v_cvt_pk_bf16_f32 v62, v64, v65
	v_cvt_pk_bf16_f32 v63, v68, v69
	global_store_dwordx4 v[56:57], v[60:63], off offset:-4096
	global_load_dwordx4 v[60:63], v[74:75], off offset:2432
	s_nop 0
	global_load_dwordx4 v[64:67], v[58:59], off offset:384
	global_load_dwordx4 v[68:71], v[74:75], off offset:384
	v_pk_mul_f32 v[58:59], v[12:13], v[50:51]
	v_pk_mul_f32 v[74:75], v[16:17], v[48:49]
	v_pk_fma_f32 v[58:59], v[4:5], v[40:41], v[58:59]
	v_pk_fma_f32 v[74:75], v[8:9], v[44:45], v[74:75]
	s_waitcnt vmcnt(2)
	v_lshlrev_b32_e32 v40, 16, v63
	s_waitcnt vmcnt(1)
	v_lshlrev_b32_e32 v42, 16, v67
	v_and_b32_e32 v43, 0xffff0000, v67
	v_and_b32_e32 v41, 0xffff0000, v63
	s_waitcnt vmcnt(0)
	v_lshlrev_b32_e32 v88, 16, v71
	v_and_b32_e32 v89, 0xffff0000, v71
	v_lshlrev_b32_e32 v44, 16, v62
	v_and_b32_e32 v45, 0xffff0000, v62
	v_lshlrev_b32_e32 v62, 16, v66
	v_and_b32_e32 v63, 0xffff0000, v66
	v_lshlrev_b32_e32 v66, 16, v70
	v_and_b32_e32 v67, 0xffff0000, v70
	v_lshlrev_b32_e32 v70, 16, v61
	v_and_b32_e32 v71, 0xffff0000, v61
	v_lshlrev_b32_e32 v90, 16, v65
	v_and_b32_e32 v91, 0xffff0000, v65
	v_lshlrev_b32_e32 v94, 16, v60
	v_and_b32_e32 v95, 0xffff0000, v60
	v_lshlrev_b32_e32 v60, 16, v64
	v_and_b32_e32 v61, 0xffff0000, v64
	v_pk_mul_f32 v[46:47], v[40:41], v[42:43]
	v_pk_mul_f32 v[44:45], v[44:45], v[62:63]
	v_pk_mul_f32 v[42:43], v[70:71], v[90:91]
	v_pk_mul_f32 v[40:41], v[94:95], v[60:61]
	v_lshlrev_b32_e32 v92, 16, v69
	v_and_b32_e32 v93, 0xffff0000, v69
	v_lshlrev_b32_e32 v64, 16, v68
	v_and_b32_e32 v65, 0xffff0000, v68
	v_pk_fma_f32 v[58:59], v[20:21], v[46:47], v[58:59]
	v_pk_fma_f32 v[60:61], v[18:19], v[44:45], v[72:73]
	v_pk_fma_f32 v[62:63], v[24:25], v[42:43], v[74:75]
	v_pk_fma_f32 v[68:69], v[22:23], v[40:41], v[86:87]
	v_pk_mul_f32 v[58:59], v[58:59], v[88:89]
	v_pk_mul_f32 v[60:61], v[60:61], v[66:67]
	v_pk_mul_f32 v[62:63], v[62:63], v[92:93]
	v_pk_mul_f32 v[64:65], v[68:69], v[64:65]
	v_mov_b32_e32 v66, v58
	v_mov_b32_e32 v67, v60
	v_mov_b32_e32 v70, v64
	v_mov_b32_e32 v71, v62
	v_mov_b32_e32 v68, v59
	v_mov_b32_e32 v69, v61
	v_mov_b32_e32 v72, v65
	v_mov_b32_e32 v73, v63
	v_pk_mul_f32 v[66:67], v[66:67], v[66:67]
	v_pk_mul_f32 v[70:71], v[70:71], v[70:71]
	v_pk_fma_f32 v[66:67], v[68:69], v[68:69], v[66:67]
	v_pk_fma_f32 v[68:69], v[72:73], v[72:73], v[70:71]
	s_nop 0
	v_add_f32_e32 v68, v68, v69
	v_add_f32_e32 v67, v67, v68
	v_add_f32_e32 v66, v66, v67
	ds_bpermute_b32 v67, v79, v66
	s_waitcnt lgkmcnt(0)
	v_add_f32_e32 v66, v66, v67
	ds_bpermute_b32 v67, v80, v66
	s_waitcnt lgkmcnt(0)
	v_add_f32_e32 v66, v66, v67
	ds_bpermute_b32 v67, v81, v66
	s_waitcnt lgkmcnt(0)
	v_add_f32_e32 v66, v66, v67
	ds_bpermute_b32 v67, v82, v66
	s_waitcnt lgkmcnt(0)
	v_add_f32_e32 v66, v66, v67
	v_fmamk_f32 v66, v66, 0x3c000000, v85
	v_mul_f32_e32 v67, 0x4b800000, v66
	v_cmp_gt_f32_e32 vcc, s19, v66
	s_nop 1
	v_cndmask_b32_e32 v66, v66, v67, vcc
	v_rsq_f32_e32 v66, v66
	s_nop 0
	v_mul_f32_e32 v67, 0x45800000, v66
	v_cndmask_b32_e32 v66, v66, v67, vcc
	v_pk_mul_f32 v[64:65], v[64:65], v[66:67] op_sel_hi:[1,0]
	v_pk_mul_f32 v[62:63], v[62:63], v[66:67] op_sel_hi:[1,0]
	v_pk_mul_f32 v[60:61], v[60:61], v[66:67] op_sel_hi:[1,0]
	v_pk_mul_f32 v[66:67], v[58:59], v[66:67] op_sel_hi:[1,0]
	v_cvt_pk_bf16_f32 v58, v64, v65
	v_cvt_pk_bf16_f32 v59, v62, v63
	v_cvt_pk_bf16_f32 v60, v60, v61
	v_cvt_pk_bf16_f32 v61, v66, v67
	global_store_dwordx4 v[56:57], v[58:61], off
	s_cbranch_scc0 .LBB0_633
	s_add_i32 s28, s28, s13
	s_cmpk_gt_i32 s28, 0x1ff
	v_add_u32_e32 v83, s14, v83
	s_cbranch_scc0 .LBB0_630
	s_cmp_eq_u32 s97, 2
	s_cbranch_scc1 .LBB0_650
.Lp4_attn:
	v_bfe_u32 v13, v0, 5, 1
	v_mov_b32_e32 v2, 0
	v_lshlrev_b32_e32 v4, 4, v13
	v_mov_b32_e32 v5, v2
	v_lshl_add_u64 v[6:7], s[82:83], 0, v[4:5]
	s_mov_b64 s[2:3], 0xc638000
	v_lshl_add_u64 v[190:191], v[6:7], 0, s[2:3]
	v_lshrrev_b32_e32 v192, 2, v0
	v_and_b32_e32 v6, 24, v78
	v_and_b32_e32 v5, 8, v78
	v_lshrrev_b32_e32 v1, 1, v0
	v_lshlrev_b32_e32 v8, 1, v5
	v_mul_u32_u24_e32 v5, 0x190, v192
	v_lshlrev_b32_e32 v7, 1, v6
	v_mov_b32_e32 v9, v2
	v_add3_u32 v193, 0, v5, v7
	v_mul_u32_u24_e32 v5, 0x88, v1
	v_and_b32_e32 v3, 31, v0
	v_lshrrev_b32_e32 v14, 7, v0
	v_lshl_add_u64 v[10:11], s[82:83], 0, v[8:9]
	s_mov_b64 s[2:3], 0xf638000
	v_add3_u32 v219, 0, v5, v8
	v_xor_b32_e32 v8, 32, v76
	v_lshl_add_u64 v[194:195], v[10:11], 0, s[2:3]
	s_movk_i32 s2, 0x190
	v_lshl_or_b32 v5, v14, 5, v3
	v_cmp_lt_i32_e32 vcc, v8, v77
	s_load_dword s13, s[6:7], 0x0
	v_bfe_u32 v15, v0, 6, 1
	v_mad_u32_u24 v5, v5, s2, 0
	v_cndmask_b32_e32 v8, v76, v8, vcc
	s_movk_i32 s2, 0x4200
	v_mov_b32_e32 v10, 0x4100
	s_add_u32 s10, s82, 0xde38000
	v_and_b32_e32 v12, 63, v0
	v_lshlrev_b32_e32 v16, 3, v13
	s_movk_i32 s8, 0x88
	v_lshl_add_u32 v7, v14, 6, 0
	v_lshlrev_b32_e32 v220, 2, v8
	v_mad_u32_u24 v8, v15, s2, 0
	v_lshl_or_b32 v10, v0, 2, v10
	s_addc_u32 s11, s83, 0
	v_add_u32_e32 v9, v7, v16
	s_movk_i32 s4, 0x80
	v_lshl_add_u32 v221, v12, 2, v8
	v_add_u32_e32 v222, v8, v10
	v_lshlrev_b32_e32 v8, 2, v13
	v_mul_u32_u24_e32 v10, 0x88, v3
	v_mad_u32_u24 v7, v3, s8, v7
	s_mov_b32 s9, 0
	v_cmp_eq_u32_e64 s[2:3], 1, v14
	v_cmp_gt_u32_e64 s[4:5], s4, v0
	v_lshl_or_b32 v223, v15, 5, v3
	s_movk_i32 s24, 0xc00
	v_mov_b64_e32 v[196:197], s[10:11]
	v_mov_b32_e32 v224, 0xc00
	v_lshlrev_b32_e32 v198, 1, v6
	v_mov_b32_e32 v199, v2
	s_mov_b64 s[10:11], 0x30000
	s_mov_b64 s[14:15], 0x80
	v_add_u32_e32 v225, v5, v4
	v_add_u32_e32 v226, v9, v10
	v_add_u32_e32 v227, v7, v16
	s_mov_b32 s25, 0xc2fc0000
	v_lshlrev_b32_e32 v200, 1, v8
	s_mov_b64 s[16:17], 0x10638800
	v_mov_b32_e32 v228, 0x358637bd
	s_mov_b32 s26, 0x800000
	s_mov_b32 s27, 0x10638000
	v_mov_b32_e32 v229, 0x42800000
	v_not_b32_e32 v230, 63
	s_mov_b32 s28, s12
	s_branch .LBB0_637

; #define RUN_PHASE(n, call) if (p.ph_lo <= (n) && (n) < p.ph_hi) { \
;     if ((n) > p.ph_lo) { if ((n) <= 7) xcd_barrier_bg(xb, smem, bg_unit); else xcd_barrier(xb); } \
;     if (PHMASK & (1 << (n))) { call; if (REPMASK & (1 << (n))) { xcd_barrier(xb); rep = 1; call; rep = 0; } } \
;     if ((n) == 7) { while (bg_unit()) {} } }
; __global__ void __launch_bounds__(256, 2) mega(Params p) {
;     ...
;   RUN_PHASE(4, (conv_items(p), phase4(p, smem)))
.LBB0_650:
	s_cmp_eq_u32 s97, 1
	s_cbranch_scc0 .Lp4_done
	s_mov_b32 s97, 2
	s_branch .LBB0_628
